# first dilated-queue index requested at the start of the workgroup's last MoBA epilogue (atomic round trip overlaps the epilogue)
# baseline (speedup 1.0000x reference)
.LBB0_328:
	s_or_b64 exec, exec, s[38:39]
	v_readlane_b32 s2, v248, 7
	v_readlane_b32 s3, v248, 8
	s_lshl_b32 s2, s2, 9
	v_readlane_b32 s3, v249, 35
	s_or_b32 s80, s2, s3
	s_lshl_b64 s[2:3], s[80:81], 2
	v_readlane_b32 s8, v250, 48
	s_add_u32 s18, s8, s2
	v_readlane_b32 s2, v250, 49
	s_addc_u32 s19, s2, s3
	s_add_u32 s12, s18, 0x1000
	s_addc_u32 s13, s19, 0
	s_mov_b64 s[78:79], 0
	s_lshr_b32 s98, s74, 3
	v_mov_b32_e32 v254, s98
	s_and_b32 s98, s74, 7
	s_sub_i32 s98, s26, s98
	s_add_i32 s98, s98, -1
	s_lshr_b32 s98, s98, 3
	s_add_i32 s98, s98, 1
	v_mov_b32_e32 v255, s98
	v_mov_b32_e32 v252, 0
	s_branch .LBB0_331
.LBB0_329:
	s_waitcnt lgkmcnt(0)
	s_barrier
	v_readfirstlane_b32 s98, v254
	s_cmp_lt_i32 s98, 64
	s_cbranch_scc1 .Lmb_noearly
	v_mov_b32_e32 v252, 1
	s_add_u32 s98, s18, 0x2000
	s_addc_u32 s99, s19, 0
	s_and_saveexec_b64 s[2:3], s[88:89]
	v_mov_b32_e32 v251, 1
	global_atomic_add v253, v2, v251, s[98:99] sc0
	s_or_b64 exec, exec, s[2:3]
.Lmb_noearly:
	ds_read_b32 v4, v92 offset:53760
	v_add_u32_e32 v16, v93, v128
	s_waitcnt vmcnt(2)
	v_mov_b64_e32 v[24:25], s[4:5]
	v_mov_b32_e32 v1, v2
	v_ashrrev_i32_e32 v17, 31, v16
	s_waitcnt lgkmcnt(0)
	v_div_scale_f32 v5, s[2:3], v4, v4, 1.0
	v_rcp_f32_e32 v7, v5
	s_movk_i32 s2, 0x10c
	v_mad_u64_u32 v[26:27], s[2:3], v93, s2, v[92:93]
	v_fma_f32 v12, -v5, v7, 1.0
	v_fmac_f32_e32 v7, v12, v7
	v_div_scale_f32 v12, vcc, 1.0, v4, 1.0
	v_mul_f32_e32 v13, v12, v7
	v_fma_f32 v15, -v5, v13, v12
	v_fmac_f32_e32 v13, v15, v7
	v_fma_f32 v5, -v5, v13, v12
	v_div_fmas_f32 v5, v5, v7, v13
	v_mad_i64_i32 v[12:13], s[2:3], v16, s93, v[24:25]
	v_lshl_add_u64 v[8:9], s[6:7], 0, v[0:1]
	s_waitcnt vmcnt(1)
	v_lshl_add_u64 v[28:29], v[12:13], 0, v[0:1]
	v_lshlrev_b64 v[12:13], 11, v[16:17]
	s_waitcnt vmcnt(0)
	v_lshl_add_u64 v[32:33], v[8:9], 0, v[12:13]
	v_lshlrev_b32_e32 v12, 3, v3
	v_mov_b32_e32 v13, v2
	v_lshl_add_u64 v[30:31], v[28:29], 0, v[12:13]
	global_load_dwordx2 v[28:29], v[30:31], off offset:1536
	s_mov_b64 s[100:101], 0x1a800
	v_lshl_add_u64 v[174:175], v[30:31], 0, s[100:101]
	global_load_dwordx2 v[160:161], v[30:31], off offset:1568
	global_load_dwordx2 v[162:163], v[30:31], off offset:1600
	global_load_dwordx2 v[164:165], v[30:31], off offset:1632
	global_load_dwordx2 v[166:167], v[174:175], off offset:1536
	global_load_dwordx2 v[168:169], v[174:175], off offset:1568
	global_load_dwordx2 v[170:171], v[174:175], off offset:1600
	global_load_dwordx2 v[172:173], v[174:175], off offset:1632
	v_div_fixup_f32 v4, v5, v4, 1.0
	v_lshl_add_u32 v5, v3, 4, v26
	ds_read_b128 v[20:23], v5 offset:18432
	v_add_u32_e32 v16, 16, v16
	s_waitcnt lgkmcnt(0)
	v_pk_mul_f32 v[20:21], v[4:5], v[20:21] op_sel_hi:[0,1]
	v_pk_mul_f32 v[22:23], v[4:5], v[22:23] op_sel_hi:[0,1]
	s_waitcnt vmcnt(0)
	v_lshlrev_b32_e32 v3, 16, v28
	v_and_b32_e32 v7, 0xffff0000, v28
	v_mul_f32_e32 v15, 0xbfb8aa3b, v3
	v_exp_f32_e32 v34, v15
	v_mul_f32_e32 v15, 0xbfb8aa3b, v7
	v_exp_f32_e32 v35, v15
	s_nop 0
	v_pk_add_f32 v[34:35], v[34:35], 1.0 op_sel_hi:[1,0]
	s_nop 0
	v_div_scale_f32 v15, s[2:3], v35, v35, v7
	v_rcp_f32_e32 v17, v15
	s_nop 0
	v_fma_f32 v19, -v15, v17, 1.0
	v_fmac_f32_e32 v17, v19, v17
	v_div_scale_f32 v19, vcc, v7, v35, v7
	v_mul_f32_e32 v27, v19, v17
	v_fma_f32 v28, -v15, v27, v19
	v_fmac_f32_e32 v27, v28, v17
	v_fma_f32 v15, -v15, v27, v19
	v_div_fmas_f32 v15, v15, v17, v27
	v_div_fixup_f32 v35, v15, v35, v7
	v_div_scale_f32 v7, s[2:3], v34, v34, v3
	v_rcp_f32_e32 v15, v7
	s_nop 0
	v_fma_f32 v17, -v7, v15, 1.0
	v_fmac_f32_e32 v15, v17, v15
	v_div_scale_f32 v17, vcc, v3, v34, v3
	v_mul_f32_e32 v19, v17, v15
	v_fma_f32 v27, -v7, v19, v17
	v_fmac_f32_e32 v19, v27, v15
	v_fma_f32 v7, -v7, v19, v17
	v_div_fmas_f32 v7, v7, v15, v19
	v_div_fixup_f32 v34, v7, v34, v3
	v_lshlrev_b32_e32 v3, 16, v29
	v_and_b32_e32 v7, 0xffff0000, v29
	v_mul_f32_e32 v15, 0xbfb8aa3b, v3
	v_exp_f32_e32 v28, v15
	v_mul_f32_e32 v15, 0xbfb8aa3b, v7
	v_exp_f32_e32 v29, v15
	v_pk_mul_f32 v[20:21], v[20:21], v[34:35]
	v_pk_add_f32 v[28:29], v[28:29], 1.0 op_sel_hi:[1,0]
	s_nop 0
	v_div_scale_f32 v15, s[2:3], v29, v29, v7
	v_rcp_f32_e32 v17, v15
	v_cvt_pk_bf16_f32 v20, v20, v21
	v_fma_f32 v19, -v15, v17, 1.0
	v_fmac_f32_e32 v17, v19, v17
	v_div_scale_f32 v19, vcc, v7, v29, v7
	v_mul_f32_e32 v21, v19, v17
	v_fma_f32 v27, -v15, v21, v19
	v_fmac_f32_e32 v21, v27, v17
	v_fma_f32 v15, -v15, v21, v19
	v_div_fmas_f32 v15, v15, v17, v21
	v_div_fixup_f32 v29, v15, v29, v7
	v_div_scale_f32 v7, s[2:3], v28, v28, v3
	v_rcp_f32_e32 v15, v7
	s_nop 0
	v_fma_f32 v17, -v7, v15, 1.0
	v_fmac_f32_e32 v15, v17, v15
	v_div_scale_f32 v17, vcc, v3, v28, v3
	v_mul_f32_e32 v19, v17, v15
	v_fma_f32 v21, -v7, v19, v17
	v_fmac_f32_e32 v19, v21, v15
	v_fma_f32 v7, -v7, v19, v17
	v_div_fmas_f32 v7, v7, v15, v19
	v_div_fixup_f32 v28, v7, v28, v3
	v_pk_mul_f32 v[22:23], v[22:23], v[28:29]
	v_lshl_add_u64 v[28:29], v[32:33], 0, v[12:13]
	v_mov_b64_e32 v[32:33], v[160:161]
	v_cvt_pk_bf16_f32 v21, v22, v23
	global_store_dwordx2 v[28:29], v[20:21], off
	ds_read_b128 v[20:23], v5 offset:18496
	s_waitcnt lgkmcnt(0)
	v_pk_mul_f32 v[20:21], v[4:5], v[20:21] op_sel_hi:[0,1]
	v_pk_mul_f32 v[22:23], v[4:5], v[22:23] op_sel_hi:[0,1]
	s_nop 0
	v_lshlrev_b32_e32 v3, 16, v32
	v_and_b32_e32 v7, 0xffff0000, v32
	v_mul_f32_e32 v15, 0xbfb8aa3b, v3
	v_exp_f32_e32 v34, v15
	v_mul_f32_e32 v15, 0xbfb8aa3b, v7
	v_exp_f32_e32 v35, v15
	s_nop 0
	v_pk_add_f32 v[34:35], v[34:35], 1.0 op_sel_hi:[1,0]
	s_nop 0
	v_div_scale_f32 v15, s[2:3], v35, v35, v7
	v_rcp_f32_e32 v17, v15
	s_nop 0
	v_fma_f32 v19, -v15, v17, 1.0
	v_fmac_f32_e32 v17, v19, v17
	v_div_scale_f32 v19, vcc, v7, v35, v7
	v_mul_f32_e32 v27, v19, v17
	v_fma_f32 v32, -v15, v27, v19
	v_fmac_f32_e32 v27, v32, v17
	v_fma_f32 v15, -v15, v27, v19
	v_div_fmas_f32 v15, v15, v17, v27
	v_div_fixup_f32 v35, v15, v35, v7
	v_div_scale_f32 v7, s[2:3], v34, v34, v3
	v_rcp_f32_e32 v15, v7
	s_nop 0
	v_fma_f32 v17, -v7, v15, 1.0
	v_fmac_f32_e32 v15, v17, v15
	v_div_scale_f32 v17, vcc, v3, v34, v3
	v_mul_f32_e32 v19, v17, v15
	v_fma_f32 v27, -v7, v19, v17
	v_fmac_f32_e32 v19, v27, v15
	v_fma_f32 v7, -v7, v19, v17
	v_div_fmas_f32 v7, v7, v15, v19
	v_div_fixup_f32 v34, v7, v34, v3
	v_lshlrev_b32_e32 v3, 16, v33
	v_and_b32_e32 v7, 0xffff0000, v33
	v_mul_f32_e32 v15, 0xbfb8aa3b, v3
	v_exp_f32_e32 v32, v15
	v_mul_f32_e32 v15, 0xbfb8aa3b, v7
	v_exp_f32_e32 v33, v15
	v_pk_mul_f32 v[20:21], v[20:21], v[34:35]
	v_pk_add_f32 v[32:33], v[32:33], 1.0 op_sel_hi:[1,0]
	s_nop 0
	v_div_scale_f32 v15, s[2:3], v33, v33, v7
	v_rcp_f32_e32 v17, v15
	v_cvt_pk_bf16_f32 v20, v20, v21
	v_fma_f32 v19, -v15, v17, 1.0
	v_fmac_f32_e32 v17, v19, v17
	v_div_scale_f32 v19, vcc, v7, v33, v7
	v_mul_f32_e32 v21, v19, v17
	v_fma_f32 v27, -v15, v21, v19
	v_fmac_f32_e32 v21, v27, v17
	v_fma_f32 v15, -v15, v21, v19
	v_div_fmas_f32 v15, v15, v17, v21
	v_div_fixup_f32 v33, v15, v33, v7
	v_div_scale_f32 v7, s[2:3], v32, v32, v3
	v_rcp_f32_e32 v15, v7
	s_nop 0
	v_fma_f32 v17, -v7, v15, 1.0
	v_fmac_f32_e32 v15, v17, v15
	v_div_scale_f32 v17, vcc, v3, v32, v3
	v_mul_f32_e32 v19, v17, v15
	v_fma_f32 v21, -v7, v19, v17
	v_fmac_f32_e32 v19, v21, v15
	v_fma_f32 v7, -v7, v19, v17
	v_div_fmas_f32 v7, v7, v15, v19
	v_div_fixup_f32 v32, v7, v32, v3
	v_pk_mul_f32 v[22:23], v[22:23], v[32:33]
	v_mov_b64_e32 v[32:33], v[162:163]
	v_cvt_pk_bf16_f32 v21, v22, v23
	v_mov_b64_e32 v[30:31], v[164:165]
	s_nop 0
	v_lshlrev_b32_e32 v3, 16, v32
	v_and_b32_e32 v7, 0xffff0000, v32
	v_mul_f32_e32 v15, 0xbfb8aa3b, v3
	v_exp_f32_e32 v34, v15
	v_mul_f32_e32 v15, 0xbfb8aa3b, v7
	v_exp_f32_e32 v35, v15
	global_store_dwordx2 v[28:29], v[20:21], off offset:32
	ds_read_b128 v[20:23], v5 offset:18560
	v_pk_add_f32 v[34:35], v[34:35], 1.0 op_sel_hi:[1,0]
	s_nop 0
	v_div_scale_f32 v15, s[2:3], v35, v35, v7
	v_rcp_f32_e32 v17, v15
	s_waitcnt lgkmcnt(0)
	v_pk_mul_f32 v[20:21], v[4:5], v[20:21] op_sel_hi:[0,1]
	v_pk_mul_f32 v[22:23], v[4:5], v[22:23] op_sel_hi:[0,1]
	v_fma_f32 v19, -v15, v17, 1.0
	v_fmac_f32_e32 v17, v19, v17
	v_div_scale_f32 v19, vcc, v7, v35, v7
	v_mul_f32_e32 v27, v19, v17
	v_fma_f32 v32, -v15, v27, v19
	v_fmac_f32_e32 v27, v32, v17
	v_fma_f32 v15, -v15, v27, v19
	v_div_fmas_f32 v15, v15, v17, v27
	v_div_fixup_f32 v35, v15, v35, v7
	v_div_scale_f32 v7, s[2:3], v34, v34, v3
	v_rcp_f32_e32 v15, v7
	s_nop 0
	v_fma_f32 v17, -v7, v15, 1.0
	v_fmac_f32_e32 v15, v17, v15
	v_div_scale_f32 v17, vcc, v3, v34, v3
	v_mul_f32_e32 v19, v17, v15
	v_fma_f32 v27, -v7, v19, v17
	v_fmac_f32_e32 v19, v27, v15
	v_fma_f32 v7, -v7, v19, v17
	v_div_fmas_f32 v7, v7, v15, v19
	v_div_fixup_f32 v34, v7, v34, v3
	v_lshlrev_b32_e32 v3, 16, v33
	v_and_b32_e32 v7, 0xffff0000, v33
	v_mul_f32_e32 v15, 0xbfb8aa3b, v3
	v_exp_f32_e32 v32, v15
	v_mul_f32_e32 v15, 0xbfb8aa3b, v7
	v_exp_f32_e32 v33, v15
	v_pk_mul_f32 v[20:21], v[20:21], v[34:35]
	v_pk_add_f32 v[32:33], v[32:33], 1.0 op_sel_hi:[1,0]
	s_nop 0
	v_div_scale_f32 v15, s[2:3], v33, v33, v7
	v_rcp_f32_e32 v17, v15
	v_cvt_pk_bf16_f32 v20, v20, v21
	v_fma_f32 v19, -v15, v17, 1.0
	v_fmac_f32_e32 v17, v19, v17
	v_div_scale_f32 v19, vcc, v7, v33, v7
	v_mul_f32_e32 v21, v19, v17
	v_fma_f32 v27, -v15, v21, v19
	v_fmac_f32_e32 v21, v27, v17
	v_fma_f32 v15, -v15, v21, v19
	v_div_fmas_f32 v15, v15, v17, v21
	v_div_fixup_f32 v33, v15, v33, v7
	v_div_scale_f32 v7, s[2:3], v32, v32, v3
	v_rcp_f32_e32 v15, v7
	s_nop 0
	v_fma_f32 v17, -v7, v15, 1.0
	v_fmac_f32_e32 v15, v17, v15
	v_div_scale_f32 v17, vcc, v3, v32, v3
	v_mul_f32_e32 v19, v17, v15
	v_fma_f32 v21, -v7, v19, v17
	v_fmac_f32_e32 v19, v21, v15
	v_fma_f32 v7, -v7, v19, v17
	v_div_fmas_f32 v7, v7, v15, v19
	v_div_fixup_f32 v32, v7, v32, v3
	s_nop 0
	v_lshlrev_b32_e32 v3, 16, v30
	v_and_b32_e32 v7, 0xffff0000, v30
	v_mul_f32_e32 v15, 0xbfb8aa3b, v3
	v_pk_mul_f32 v[22:23], v[22:23], v[32:33]
	v_exp_f32_e32 v32, v15
	v_mul_f32_e32 v15, 0xbfb8aa3b, v7
	v_exp_f32_e32 v33, v15
	v_cvt_pk_bf16_f32 v21, v22, v23
	global_store_dwordx2 v[28:29], v[20:21], off offset:64
	ds_read_b128 v[20:23], v5 offset:18624
	v_pk_add_f32 v[32:33], v[32:33], 1.0 op_sel_hi:[1,0]
	s_waitcnt lgkmcnt(0)
	v_pk_mul_f32 v[20:21], v[4:5], v[20:21] op_sel_hi:[0,1]
	v_div_scale_f32 v15, s[2:3], v33, v33, v7
	v_rcp_f32_e32 v17, v15
	v_pk_mul_f32 v[22:23], v[4:5], v[22:23] op_sel_hi:[0,1]
	v_fma_f32 v19, -v15, v17, 1.0
	v_fmac_f32_e32 v17, v19, v17
	v_div_scale_f32 v19, vcc, v7, v33, v7
	v_mul_f32_e32 v27, v19, v17
	v_fma_f32 v30, -v15, v27, v19
	v_fmac_f32_e32 v27, v30, v17
	v_fma_f32 v15, -v15, v27, v19
	v_div_fmas_f32 v15, v15, v17, v27
	v_div_fixup_f32 v33, v15, v33, v7
	v_div_scale_f32 v7, s[2:3], v32, v32, v3
	v_rcp_f32_e32 v15, v7
	s_nop 0
	v_fma_f32 v17, -v7, v15, 1.0
	v_fmac_f32_e32 v15, v17, v15
	v_div_scale_f32 v17, vcc, v3, v32, v3
	v_mul_f32_e32 v19, v17, v15
	v_fma_f32 v27, -v7, v19, v17
	v_fmac_f32_e32 v19, v27, v15
	v_fma_f32 v7, -v7, v19, v17
	v_div_fmas_f32 v7, v7, v15, v19
	v_div_fixup_f32 v32, v7, v32, v3
	v_lshlrev_b32_e32 v3, 16, v31
	v_and_b32_e32 v7, 0xffff0000, v31
	v_mul_f32_e32 v15, 0xbfb8aa3b, v3
	v_mul_f32_e32 v4, 0xbfb8aa3b, v7
	v_exp_f32_e32 v30, v15
	v_exp_f32_e32 v31, v4
	v_pk_mul_f32 v[20:21], v[20:21], v[32:33]
	v_pk_add_f32 v[30:31], v[30:31], 1.0 op_sel_hi:[1,0]
	s_nop 0
	v_div_scale_f32 v4, s[2:3], v31, v31, v7
	v_rcp_f32_e32 v15, v4
	v_cvt_pk_bf16_f32 v20, v20, v21
	v_fma_f32 v17, -v4, v15, 1.0
	v_fmac_f32_e32 v15, v17, v15
	v_div_scale_f32 v17, vcc, v7, v31, v7
	v_mul_f32_e32 v19, v17, v15
	v_fma_f32 v21, -v4, v19, v17
	v_fmac_f32_e32 v19, v21, v15
	v_fma_f32 v4, -v4, v19, v17
	v_div_fmas_f32 v4, v4, v15, v19
	v_div_fixup_f32 v31, v4, v31, v7
	v_div_scale_f32 v4, s[2:3], v30, v30, v3
	v_rcp_f32_e32 v7, v4
	s_movk_i32 s2, 0xfef4
	v_fma_f32 v15, -v4, v7, 1.0
	v_fmac_f32_e32 v7, v15, v7
	v_div_scale_f32 v15, vcc, v3, v30, v3
	v_mul_f32_e32 v17, v15, v7
	v_fma_f32 v19, -v4, v17, v15
	v_fmac_f32_e32 v17, v19, v7
	v_fma_f32 v4, -v4, v17, v15
	v_div_fmas_f32 v4, v4, v7, v17
	v_div_fixup_f32 v30, v4, v30, v3
	v_pk_mul_f32 v[22:23], v[22:23], v[30:31]
	s_nop 0
	v_cvt_pk_bf16_f32 v21, v22, v23
	global_store_dwordx2 v[28:29], v[20:21], off offset:96
	v_mad_u64_u32 v[20:21], s[2:3], v93, s2, v[26:27]
	ds_read_b32 v3, v20 offset:53824
	v_mad_i64_i32 v[20:21], s[2:3], v16, s93, v[24:25]
	v_lshl_add_u64 v[0:1], v[20:21], 0, v[0:1]
	ds_read_b128 v[20:23], v5 offset:22784
	s_waitcnt lgkmcnt(1)
	v_div_scale_f32 v4, s[2:3], v3, v3, 1.0
	v_rcp_f32_e32 v7, v4
	s_nop 0
	v_fma_f32 v15, -v4, v7, 1.0
	v_fmac_f32_e32 v7, v15, v7
	v_div_scale_f32 v15, vcc, 1.0, v3, 1.0
	v_mul_f32_e32 v17, v15, v7
	v_fma_f32 v19, -v4, v17, v15
	v_fmac_f32_e32 v17, v19, v7
	v_fma_f32 v4, -v4, v17, v15
	v_div_fmas_f32 v4, v4, v7, v17
	v_ashrrev_i32_e32 v17, 31, v16
	v_lshlrev_b64 v[16:17], 11, v[16:17]
	v_lshl_add_u64 v[16:17], v[8:9], 0, v[16:17]
	v_lshl_add_u64 v[8:9], v[0:1], 0, v[12:13]
	v_mov_b64_e32 v[0:1], v[166:167]
	v_div_fixup_f32 v4, v4, v3, 1.0
	s_waitcnt lgkmcnt(0)
	v_pk_mul_f32 v[20:21], v[4:5], v[20:21] op_sel_hi:[0,1]
	v_pk_mul_f32 v[22:23], v[4:5], v[22:23] op_sel_hi:[0,1]
	s_nop 0
	v_lshlrev_b32_e32 v3, 16, v0
	v_and_b32_e32 v0, 0xffff0000, v0
	v_mul_f32_e32 v7, 0xbfb8aa3b, v3
	v_exp_f32_e32 v24, v7
	v_mul_f32_e32 v7, 0xbfb8aa3b, v0
	v_exp_f32_e32 v25, v7
	s_nop 0
	v_pk_add_f32 v[24:25], v[24:25], 1.0 op_sel_hi:[1,0]
	s_nop 0
	v_div_scale_f32 v7, s[2:3], v25, v25, v0
	v_rcp_f32_e32 v15, v7
	s_nop 0
	v_fma_f32 v19, -v7, v15, 1.0
	v_fmac_f32_e32 v15, v19, v15
	v_div_scale_f32 v19, vcc, v0, v25, v0
	v_mul_f32_e32 v26, v19, v15
	v_fma_f32 v27, -v7, v26, v19
	v_fmac_f32_e32 v26, v27, v15
	v_fma_f32 v7, -v7, v26, v19
	v_div_fmas_f32 v7, v7, v15, v26
	v_div_fixup_f32 v25, v7, v25, v0
	v_div_scale_f32 v0, s[2:3], v24, v24, v3
	v_rcp_f32_e32 v7, v0
	s_nop 0
	v_fma_f32 v15, -v0, v7, 1.0
	v_fmac_f32_e32 v7, v15, v7
	v_div_scale_f32 v15, vcc, v3, v24, v3
	v_mul_f32_e32 v19, v15, v7
	v_fma_f32 v26, -v0, v19, v15
	v_fmac_f32_e32 v19, v26, v7
	v_fma_f32 v0, -v0, v19, v15
	v_div_fmas_f32 v0, v0, v7, v19
	v_div_fixup_f32 v24, v0, v24, v3
	v_lshlrev_b32_e32 v3, 16, v1
	v_and_b32_e32 v7, 0xffff0000, v1
	v_mul_f32_e32 v0, 0xbfb8aa3b, v3
	v_mul_f32_e32 v1, 0xbfb8aa3b, v7
	v_exp_f32_e32 v0, v0
	v_exp_f32_e32 v1, v1
	v_pk_mul_f32 v[20:21], v[20:21], v[24:25]
	v_pk_add_f32 v[0:1], v[0:1], 1.0 op_sel_hi:[1,0]
	s_nop 0
	v_div_scale_f32 v15, s[2:3], v1, v1, v7
	v_rcp_f32_e32 v19, v15
	v_cvt_pk_bf16_f32 v20, v20, v21
	v_fma_f32 v21, -v15, v19, 1.0
	v_fmac_f32_e32 v19, v21, v19
	v_div_scale_f32 v21, vcc, v7, v1, v7
	v_mul_f32_e32 v24, v21, v19
	v_fma_f32 v25, -v15, v24, v21
	v_fmac_f32_e32 v24, v25, v19
	v_fma_f32 v15, -v15, v24, v21
	v_div_fmas_f32 v15, v15, v19, v24
	v_div_fixup_f32 v1, v15, v1, v7
	v_div_scale_f32 v7, s[2:3], v0, v0, v3
	v_rcp_f32_e32 v15, v7
	s_nop 0
	v_fma_f32 v19, -v7, v15, 1.0
	v_fmac_f32_e32 v15, v19, v15
	v_div_scale_f32 v19, vcc, v3, v0, v3
	v_mul_f32_e32 v21, v19, v15
	v_fma_f32 v24, -v7, v21, v19
	v_fmac_f32_e32 v21, v24, v15
	v_fma_f32 v7, -v7, v21, v19
	v_div_fmas_f32 v7, v7, v15, v21
	v_div_fixup_f32 v0, v7, v0, v3
	v_pk_mul_f32 v[0:1], v[22:23], v[0:1]
	s_nop 0
	v_cvt_pk_bf16_f32 v21, v0, v1
	v_lshl_add_u64 v[0:1], v[16:17], 0, v[12:13]
	v_mov_b64_e32 v[12:13], v[168:169]
	s_nop 0
	v_lshlrev_b32_e32 v3, 16, v12
	v_and_b32_e32 v7, 0xffff0000, v12
	v_mul_f32_e32 v12, 0xbfb8aa3b, v3
	v_exp_f32_e32 v16, v12
	v_mul_f32_e32 v12, 0xbfb8aa3b, v7
	v_exp_f32_e32 v17, v12
	global_store_dwordx2 v[0:1], v[20:21], off
	ds_read_b128 v[20:23], v5 offset:22848
	v_pk_add_f32 v[16:17], v[16:17], 1.0 op_sel_hi:[1,0]
	s_nop 0
	v_div_scale_f32 v12, s[2:3], v17, v17, v7
	v_rcp_f32_e32 v15, v12
	s_waitcnt lgkmcnt(0)
	v_pk_mul_f32 v[20:21], v[4:5], v[20:21] op_sel_hi:[0,1]
	v_fma_f32 v19, -v12, v15, 1.0
	v_fmac_f32_e32 v15, v19, v15
	v_div_scale_f32 v19, vcc, v7, v17, v7
	v_mul_f32_e32 v24, v19, v15
	v_fma_f32 v25, -v12, v24, v19
	v_fmac_f32_e32 v24, v25, v15
	v_fma_f32 v12, -v12, v24, v19
	v_div_fmas_f32 v12, v12, v15, v24
	v_div_fixup_f32 v17, v12, v17, v7
	v_div_scale_f32 v7, s[2:3], v16, v16, v3
	v_rcp_f32_e32 v12, v7
	s_nop 0
	v_fma_f32 v15, -v7, v12, 1.0
	v_fmac_f32_e32 v12, v15, v12
	v_div_scale_f32 v15, vcc, v3, v16, v3
	v_mul_f32_e32 v19, v15, v12
	v_fma_f32 v24, -v7, v19, v15
	v_fmac_f32_e32 v19, v24, v12
	v_fma_f32 v7, -v7, v19, v15
	v_div_fmas_f32 v7, v7, v12, v19
	v_div_fixup_f32 v16, v7, v16, v3
	v_lshlrev_b32_e32 v3, 16, v13
	v_pk_mul_f32 v[16:17], v[20:21], v[16:17]
	v_and_b32_e32 v7, 0xffff0000, v13
	v_mul_f32_e32 v13, 0xbfb8aa3b, v3
	v_cvt_pk_bf16_f32 v12, v16, v17
	v_exp_f32_e32 v16, v13
	v_mul_f32_e32 v13, 0xbfb8aa3b, v7
	v_exp_f32_e32 v17, v13
	v_pk_mul_f32 v[20:21], v[4:5], v[22:23] op_sel_hi:[0,1]
	v_pk_add_f32 v[16:17], v[16:17], 1.0 op_sel_hi:[1,0]
	s_nop 0
	v_div_scale_f32 v13, s[2:3], v17, v17, v7
	v_rcp_f32_e32 v15, v13
	s_nop 0
	v_fma_f32 v19, -v13, v15, 1.0
	v_fmac_f32_e32 v15, v19, v15
	v_div_scale_f32 v19, vcc, v7, v17, v7
	v_mul_f32_e32 v22, v19, v15
	v_fma_f32 v23, -v13, v22, v19
	v_fmac_f32_e32 v22, v23, v15
	v_fma_f32 v13, -v13, v22, v19
	v_div_fmas_f32 v13, v13, v15, v22
	v_div_fixup_f32 v17, v13, v17, v7
	v_div_scale_f32 v7, s[2:3], v16, v16, v3
	v_rcp_f32_e32 v13, v7
	s_nop 0
	v_fma_f32 v15, -v7, v13, 1.0
	v_fmac_f32_e32 v13, v15, v13
	v_div_scale_f32 v15, vcc, v3, v16, v3
	v_mul_f32_e32 v19, v15, v13
	v_fma_f32 v22, -v7, v19, v15
	v_fmac_f32_e32 v19, v22, v13
	v_fma_f32 v7, -v7, v19, v15
	v_div_fmas_f32 v7, v7, v13, v19
	v_div_fixup_f32 v16, v7, v16, v3
	v_pk_mul_f32 v[16:17], v[20:21], v[16:17]
	ds_read_b128 v[20:23], v5 offset:22912
	v_cvt_pk_bf16_f32 v13, v16, v17
	global_store_dwordx2 v[0:1], v[12:13], off offset:32
	v_mov_b64_e32 v[12:13], v[170:171]
	s_waitcnt lgkmcnt(0)
	v_pk_mul_f32 v[20:21], v[4:5], v[20:21] op_sel_hi:[0,1]
	v_mov_b64_e32 v[8:9], v[172:173]
	s_nop 0
	v_lshlrev_b32_e32 v3, 16, v12
	v_and_b32_e32 v7, 0xffff0000, v12
	v_mul_f32_e32 v12, 0xbfb8aa3b, v3
	v_exp_f32_e32 v16, v12
	v_mul_f32_e32 v12, 0xbfb8aa3b, v7
	v_exp_f32_e32 v17, v12
	s_nop 0
	v_pk_add_f32 v[16:17], v[16:17], 1.0 op_sel_hi:[1,0]
	s_nop 0
	v_div_scale_f32 v12, s[2:3], v17, v17, v7
	v_rcp_f32_e32 v15, v12
	s_nop 0
	v_fma_f32 v19, -v12, v15, 1.0
	v_fmac_f32_e32 v15, v19, v15
	v_div_scale_f32 v19, vcc, v7, v17, v7
	v_mul_f32_e32 v24, v19, v15
	v_fma_f32 v25, -v12, v24, v19
	v_fmac_f32_e32 v24, v25, v15
	v_fma_f32 v12, -v12, v24, v19
	v_div_fmas_f32 v12, v12, v15, v24
	v_div_fixup_f32 v17, v12, v17, v7
	v_div_scale_f32 v7, s[2:3], v16, v16, v3
	v_rcp_f32_e32 v12, v7
	s_nop 0
	v_fma_f32 v15, -v7, v12, 1.0
	v_fmac_f32_e32 v12, v15, v12
	v_div_scale_f32 v15, vcc, v3, v16, v3
	v_mul_f32_e32 v19, v15, v12
	v_fma_f32 v24, -v7, v19, v15
	v_fmac_f32_e32 v19, v24, v12
	v_fma_f32 v7, -v7, v19, v15
	v_div_fmas_f32 v7, v7, v12, v19
	v_div_fixup_f32 v16, v7, v16, v3
	v_lshlrev_b32_e32 v3, 16, v13
	v_pk_mul_f32 v[16:17], v[20:21], v[16:17]
	v_and_b32_e32 v7, 0xffff0000, v13
	v_mul_f32_e32 v13, 0xbfb8aa3b, v3
	v_cvt_pk_bf16_f32 v12, v16, v17
	v_exp_f32_e32 v16, v13
	v_mul_f32_e32 v13, 0xbfb8aa3b, v7
	v_exp_f32_e32 v17, v13
	v_pk_mul_f32 v[20:21], v[4:5], v[22:23] op_sel_hi:[0,1]
	v_pk_add_f32 v[16:17], v[16:17], 1.0 op_sel_hi:[1,0]
	s_nop 0
	v_div_scale_f32 v13, s[2:3], v17, v17, v7
	v_rcp_f32_e32 v15, v13
	s_nop 0
	v_fma_f32 v19, -v13, v15, 1.0
	v_fmac_f32_e32 v15, v19, v15
	v_div_scale_f32 v19, vcc, v7, v17, v7
	v_mul_f32_e32 v22, v19, v15
	v_fma_f32 v23, -v13, v22, v19
	v_fmac_f32_e32 v22, v23, v15
	v_fma_f32 v13, -v13, v22, v19
	v_div_fmas_f32 v13, v13, v15, v22
	v_div_fixup_f32 v17, v13, v17, v7
	v_div_scale_f32 v7, s[2:3], v16, v16, v3
	v_rcp_f32_e32 v13, v7
	s_nop 0
	v_fma_f32 v15, -v7, v13, 1.0
	v_fmac_f32_e32 v13, v15, v13
	v_div_scale_f32 v15, vcc, v3, v16, v3
	v_mul_f32_e32 v19, v15, v13
	v_fma_f32 v22, -v7, v19, v15
	v_fmac_f32_e32 v19, v22, v13
	v_fma_f32 v7, -v7, v19, v15
	v_div_fmas_f32 v7, v7, v13, v19
	v_div_fixup_f32 v16, v7, v16, v3
	v_pk_mul_f32 v[16:17], v[20:21], v[16:17]
	s_nop 0
	v_lshlrev_b32_e32 v3, 16, v8
	v_cvt_pk_bf16_f32 v13, v16, v17
	ds_read_b128 v[20:23], v5 offset:22976
	v_and_b32_e32 v5, 0xffff0000, v8
	v_mul_f32_e32 v7, 0xbfb8aa3b, v3
	global_store_dwordx2 v[0:1], v[12:13], off offset:64
	v_exp_f32_e32 v12, v7
	v_mul_f32_e32 v7, 0xbfb8aa3b, v5
	v_exp_f32_e32 v13, v7
	s_waitcnt lgkmcnt(0)
	v_pk_mul_f32 v[16:17], v[4:5], v[20:21] op_sel_hi:[0,1]
	v_pk_add_f32 v[12:13], v[12:13], 1.0 op_sel_hi:[1,0]
	s_nop 0
	v_div_scale_f32 v7, s[2:3], v13, v13, v5
	v_rcp_f32_e32 v8, v7
	s_nop 0
	v_fma_f32 v15, -v7, v8, 1.0
	v_fmac_f32_e32 v8, v15, v8
	v_div_scale_f32 v15, vcc, v5, v13, v5
	v_mul_f32_e32 v19, v15, v8
	v_fma_f32 v20, -v7, v19, v15
	v_fmac_f32_e32 v19, v20, v8
	v_fma_f32 v7, -v7, v19, v15
	v_div_fmas_f32 v7, v7, v8, v19
	v_div_fixup_f32 v13, v7, v13, v5
	v_div_scale_f32 v5, s[2:3], v12, v12, v3
	v_rcp_f32_e32 v7, v5
	s_nop 0
	v_fma_f32 v8, -v5, v7, 1.0
	v_fmac_f32_e32 v7, v8, v7
	v_div_scale_f32 v8, vcc, v3, v12, v3
	v_mul_f32_e32 v15, v8, v7
	v_fma_f32 v19, -v5, v15, v8
	v_fmac_f32_e32 v15, v19, v7
	v_fma_f32 v5, -v5, v15, v8
	v_div_fmas_f32 v5, v5, v7, v15
	v_div_fixup_f32 v12, v5, v12, v3
	v_lshlrev_b32_e32 v3, 16, v9
	v_and_b32_e32 v7, 0xffff0000, v9
	v_pk_mul_f32 v[12:13], v[16:17], v[12:13]
	v_mul_f32_e32 v5, 0xbfb8aa3b, v3
	v_mul_f32_e32 v9, 0xbfb8aa3b, v7
	v_cvt_pk_bf16_f32 v8, v12, v13
	v_exp_f32_e32 v12, v5
	v_exp_f32_e32 v13, v9
	v_pk_mul_f32 v[4:5], v[4:5], v[22:23] op_sel_hi:[0,1]
	v_pk_add_f32 v[12:13], v[12:13], 1.0 op_sel_hi:[1,0]
	s_nop 0
	v_div_scale_f32 v9, s[2:3], v13, v13, v7
	v_rcp_f32_e32 v15, v9
	s_nop 0
	v_fma_f32 v16, -v9, v15, 1.0
	v_fmac_f32_e32 v15, v16, v15
	v_div_scale_f32 v16, vcc, v7, v13, v7
	v_mul_f32_e32 v17, v16, v15
	v_fma_f32 v19, -v9, v17, v16
	v_fmac_f32_e32 v17, v19, v15
	v_fma_f32 v9, -v9, v17, v16
	v_div_fmas_f32 v9, v9, v15, v17
	v_div_fixup_f32 v13, v9, v13, v7
	v_div_scale_f32 v7, s[2:3], v12, v12, v3
	v_rcp_f32_e32 v9, v7
	s_xor_b64 s[2:3], exec, -1
	v_fma_f32 v15, -v7, v9, 1.0
	v_fmac_f32_e32 v9, v15, v9
	v_div_scale_f32 v15, vcc, v3, v12, v3
	v_mul_f32_e32 v16, v15, v9
	v_fma_f32 v17, -v7, v16, v15
	v_fmac_f32_e32 v16, v17, v9
	v_fma_f32 v7, -v7, v16, v15
	v_div_fmas_f32 v7, v7, v9, v16
	v_div_fixup_f32 v12, v7, v12, v3
	v_pk_mul_f32 v[4:5], v[4:5], v[12:13]
	s_nop 0
	v_cvt_pk_bf16_f32 v9, v4, v5
	global_store_dwordx2 v[0:1], v[8:9], off offset:96

.LBB0_436:
	s_or_b64 exec, exec, s[78:79]
	s_add_u32 s12, s18, 0x2000
	s_addc_u32 s13, s19, 0
	s_mov_b64 s[42:43], 0
	v_readfirstlane_b32 s98, v252
	s_cmp_lg_u32 s98, 0
	s_cbranch_scc1 .Ldil_first_done
	s_and_saveexec_b64 s[2:3], s[88:89]
	v_mov_b32_e32 v1, 1
	global_atomic_add v253, v2, v1, s[12:13] sc0
	s_or_b64 exec, exec, s[2:3]
.Ldil_first_done:
	v_mov_b32_e32 v252, 0
	s_branch .LBB0_439
